# v36 + layer-0 out/ff1/ff2 weight transposes moved from prologue to idle WGs of in-proj-0 last round
# speedup vs baseline: 1.0015x; 1.0015x over previous
.LBB0_6:
	s_add_u32 s54, s88, 0xe400000
	s_addc_u32 s55, s89, 0
	s_add_u32 s4, s88, 0x100000
	s_addc_u32 s5, s89, 0
	v_writelane_b32 v251, s4, 3
	s_cmp_gt_i32 s90, -1
	s_load_dwordx16 s[12:27], s[0:1], 0x40
	v_writelane_b32 v251, s5, 4
	s_cselect_b64 s[4:5], -1, 0
	s_add_u32 s96, s0, 0xd0
	v_writelane_b32 v251, s4, 5
	s_addc_u32 s97, s1, 0
	v_lshrrev_b32_e32 v1, 20, v0
	v_writelane_b32 v251, s5, 6
	s_add_u32 s4, s88, 0x1200
	s_addc_u32 s5, s89, 0
	v_writelane_b32 v251, s4, 7
	v_lshrrev_b32_e32 v0, 10, v0
	v_or_b32_e32 v0, v0, v1
	v_writelane_b32 v251, s5, 8
	s_add_u32 s4, s88, 0x1400
	s_addc_u32 s5, s89, 0
	v_writelane_b32 v251, s4, 9
	s_load_dwordx16 s[72:87], s[0:1], 0x0
	s_load_dwordx16 s[56:71], s[0:1], 0x80
	v_writelane_b32 v251, s5, 10
	s_add_u32 s4, s88, 0x1500
	s_addc_u32 s5, s89, 0
	v_writelane_b32 v251, s4, 11
	s_brev_b32 s0, 1
	v_mov_b32_e32 v1, 0
	v_writelane_b32 v251, s5, 12
	s_add_u32 s4, s88, 0x1600
	s_addc_u32 s5, s89, 0
	v_writelane_b32 v251, s4, 13
	v_mbcnt_lo_u32_b32 v2, -1, 0
	v_mov_b32_e32 v157, 1
	v_writelane_b32 v251, s5, 14
	s_add_u32 s4, s88, 0x1700
	s_addc_u32 s5, s89, 0
	v_writelane_b32 v251, s4, 15
	v_mov_b32_e32 v218, 0x358637bd
	v_mov_b32_e32 v219, 0x1f8
	v_writelane_b32 v251, s5, 16
	s_add_u32 s4, s88, 0x1800
	s_addc_u32 s5, s89, 0
	v_writelane_b32 v251, s4, 17
	v_mov_b32_e32 v154, 0xbf1f24be
	v_mov_b32_e32 v156, 0x3e642e9d
	v_writelane_b32 v251, s5, 18
	s_add_u32 s4, s88, 0x1900
	s_addc_u32 s5, s89, 0
	v_writelane_b32 v251, s4, 19
	v_mbcnt_hi_u32_b32 v220, -1, v2
	v_mov_b32_e32 v250, 0x100
	v_writelane_b32 v251, s5, 20
	s_add_u32 s4, s88, 0x1a00
	s_addc_u32 s5, s89, 0
	v_writelane_b32 v251, s4, 21
	v_mov_b32_e32 v221, 0x200
	v_mov_b32_e32 v228, 0x80
	v_writelane_b32 v251, s5, 22
	s_add_u32 s4, s88, 0x1b00
	s_addc_u32 s5, s89, 0
	v_writelane_b32 v251, s4, 23
	v_mov_b32_e32 v229, 0x42800000
	v_not_b32_e32 v230, 63
	v_writelane_b32 v251, s5, 24
	s_add_u32 s4, s88, 0x1c00
	s_addc_u32 s5, s89, 0
	v_writelane_b32 v251, s4, 25
	v_mov_b64_e32 v[158:159], 0x550
	v_mov_b64_e32 v[160:161], 0x54f
	v_writelane_b32 v251, s5, 26
	s_add_u32 s4, s88, 0x1d00
	s_addc_u32 s5, s89, 0
	v_writelane_b32 v251, s4, 27
	v_mov_b64_e32 v[162:163], 0x200
	v_mov_b64_e32 v[164:165], 0x1ff
	v_writelane_b32 v251, s5, 28
	s_add_u32 s4, s88, 0x1e00
	s_addc_u32 s5, s89, 0
	v_writelane_b32 v251, s4, 29
	v_mov_b32_e32 v231, 0x7f800000
	v_mov_b32_e32 v232, 0x7fc00000
	v_writelane_b32 v251, s5, 30
	s_add_u32 s4, s88, 0x1f00
	s_addc_u32 s5, s89, 0
	v_writelane_b32 v251, s4, 31
	s_mov_b32 s40, 0x8000
	s_movk_i32 s33, 0x6000
	v_writelane_b32 v251, s5, 32
	s_add_u32 s4, s88, 0x2000
	s_addc_u32 s5, s89, 0
	v_writelane_b32 v251, s4, 33
	s_nop 1
	v_writelane_b32 v251, s5, 34
	s_add_u32 s4, s88, 0x2100
	s_addc_u32 s5, s89, 0
	v_writelane_b32 v251, s4, 35
	s_nop 1
	v_writelane_b32 v251, s5, 36
	s_add_u32 s4, s88, 0x2200
	s_addc_u32 s5, s89, 0
	v_writelane_b32 v251, s4, 37
	s_nop 1
	v_writelane_b32 v251, s5, 38
	s_add_u32 s4, s88, 0x2300
	s_addc_u32 s5, s89, 0
	v_writelane_b32 v251, s4, 39
	s_cmp_eq_u32 s8, 15
	s_nop 0
	v_writelane_b32 v251, s5, 40
	s_cselect_b64 s[4:5], -1, 0
	v_writelane_b32 v251, s4, 41
	s_cmp_eq_u32 s8, 14
	s_nop 0
	v_writelane_b32 v251, s5, 42
	s_cselect_b64 s[4:5], -1, 0
	v_writelane_b32 v251, s4, 43
	s_cmp_eq_u32 s8, 13
	s_nop 0
	v_writelane_b32 v251, s5, 44
	s_cselect_b64 s[4:5], -1, 0
	v_writelane_b32 v251, s4, 45
	s_cmp_eq_u32 s8, 12
	s_nop 0
	v_writelane_b32 v251, s5, 46
	s_cselect_b64 s[4:5], -1, 0
	v_writelane_b32 v251, s4, 47
	s_cmp_eq_u32 s8, 11
	s_nop 0
	v_writelane_b32 v251, s5, 48
	s_cselect_b64 s[4:5], -1, 0
	v_writelane_b32 v251, s4, 49
	s_cmp_eq_u32 s8, 10
	s_nop 0
	v_writelane_b32 v251, s5, 50
	s_cselect_b64 s[4:5], -1, 0
	v_writelane_b32 v251, s4, 51
	s_cmp_eq_u32 s8, 9
	s_nop 0
	v_writelane_b32 v251, s5, 52
	s_cselect_b64 s[4:5], -1, 0
	v_writelane_b32 v251, s4, 53
	s_cmp_eq_u32 s8, 8
	s_nop 0
	v_writelane_b32 v251, s5, 54
	s_cselect_b64 s[4:5], -1, 0
	v_writelane_b32 v251, s4, 55
	s_cmp_eq_u32 s8, 7
	s_nop 0
	v_writelane_b32 v251, s5, 56
	s_cselect_b64 s[4:5], -1, 0
	v_writelane_b32 v251, s4, 57
	s_cmp_eq_u32 s8, 6
	s_nop 0
	v_writelane_b32 v251, s5, 58
	s_cselect_b64 s[4:5], -1, 0
	v_writelane_b32 v251, s4, 59
	s_cmp_eq_u32 s8, 5
	s_nop 0
	v_writelane_b32 v251, s5, 60
	s_cselect_b64 s[4:5], -1, 0
	v_writelane_b32 v251, s4, 61
	s_cmp_eq_u32 s8, 4
	s_nop 0
	v_writelane_b32 v251, s5, 62
	s_cselect_b64 s[4:5], -1, 0
	v_writelane_b32 v251, s4, 63
	s_cmp_eq_u32 s8, 3
	v_readlane_b32 s9, v251, 0
	v_writelane_b32 v252, s5, 0
	s_cselect_b64 s[4:5], -1, 0
	v_writelane_b32 v252, s4, 1
	s_cmp_eq_u32 s8, 2
	s_nop 0
	v_writelane_b32 v252, s5, 2
	s_cselect_b64 s[4:5], -1, 0
	v_writelane_b32 v252, s4, 3
	s_cmp_eq_u32 s8, 1
	s_nop 0
	v_writelane_b32 v252, s5, 4
	s_cselect_b64 s[4:5], -1, 0
	v_writelane_b32 v252, s4, 5
	s_cmp_eq_u32 s8, 0
	s_nop 0
	v_writelane_b32 v252, s5, 6
	s_cselect_b64 s[4:5], -1, 0
	v_writelane_b32 v252, s4, 7
	s_nop 1
	v_writelane_b32 v252, s5, 8
	s_lshl_b32 s4, s8, 8
	s_add_u32 s2, s2, s4
	s_addc_u32 s3, s3, 0
	s_add_u32 s4, s2, 0x1400
	s_addc_u32 s5, s3, 0
	v_writelane_b32 v252, s4, 9
	s_add_u32 s2, s2, 0x2400
	s_addc_u32 s3, s3, 0
	v_writelane_b32 v252, s5, 10
	v_writelane_b32 v252, s2, 11
	s_nop 1
	v_writelane_b32 v252, s3, 12
	s_add_u32 s2, s88, 0x4400
	s_addc_u32 s3, s89, 0
	v_writelane_b32 v252, s2, 13
	s_nop 1
	v_writelane_b32 v252, s3, 14
	s_add_u32 s2, s88, 0x4500
	s_addc_u32 s3, s89, 0
	v_writelane_b32 v252, s2, 15
	s_nop 1
	v_writelane_b32 v252, s3, 16
	s_lshl_b32 s2, s9, 3
	s_cmp_eq_u32 s9, 0
	v_writelane_b32 v252, s2, 17
	s_cselect_b64 s[2:3], -1, 0
	v_writelane_b32 v252, s2, 18
	s_nop 1
	v_writelane_b32 v252, s3, 19
	s_add_u32 s2, s88, 0x8000
	s_addc_u32 s3, s89, 0
	v_writelane_b32 v252, s2, 20
	s_add_u32 s42, s88, 0x240000
	s_addc_u32 s43, s89, 0
	v_writelane_b32 v252, s3, 21
	s_lshl_b32 s2, s9, 9
	s_cmpk_lt_i32 s9, 0x200
	v_writelane_b32 v252, s2, 22
	s_cselect_b64 s[2:3], -1, 0
	v_writelane_b32 v252, s2, 23
	s_nop 1
	v_writelane_b32 v252, s3, 24
	s_add_u32 s2, s88, 0x6000000
	s_addc_u32 s3, s89, 0
	v_writelane_b32 v252, s2, 25
	s_nop 1
	v_writelane_b32 v252, s3, 26
	s_add_u32 s2, s88, 0x200000
	s_addc_u32 s3, s89, 0
	v_writelane_b32 v252, s2, 27
	s_cmpk_lt_i32 s9, 0x100
	s_nop 0
	v_writelane_b32 v252, s3, 28
	s_cselect_b64 s[2:3], -1, 0
	v_writelane_b32 v252, s2, 29
	s_nop 1
	v_writelane_b32 v252, s3, 30
	s_add_u32 s2, s88, 0x400000
	v_writelane_b32 v252, s2, 31
	s_addc_u32 s2, s89, 0
	s_cmpk_lt_i32 s9, 0x80
	v_writelane_b32 v252, s2, 32
	s_cselect_b64 s[2:3], -1, 0
	v_writelane_b32 v252, s2, 33
	s_nop 1
	v_writelane_b32 v252, s3, 34
	s_waitcnt lgkmcnt(0)
	v_writelane_b32 v252, s12, 35
	s_add_u32 s2, s12, 0x400
	s_addc_u32 s3, s13, 0
	v_writelane_b32 v252, s13, 36
	v_writelane_b32 v252, s14, 37
	v_writelane_b32 v252, s15, 38
	v_writelane_b32 v252, s16, 39
	v_writelane_b32 v252, s17, 40
	v_writelane_b32 v252, s18, 41
	v_writelane_b32 v252, s19, 42
	v_writelane_b32 v252, s20, 43
	v_writelane_b32 v252, s21, 44
	v_writelane_b32 v252, s22, 45
	v_writelane_b32 v252, s23, 46
	v_writelane_b32 v252, s24, 47
	v_writelane_b32 v252, s25, 48
	v_writelane_b32 v252, s26, 49
	v_writelane_b32 v252, s27, 50
	v_writelane_b32 v252, s2, 51
	s_cmpk_lt_i32 s9, 0x300
	s_mov_b32 s21, 0
	v_writelane_b32 v252, s3, 52
	s_cselect_b64 s[2:3], -1, 0
	s_add_u32 s10, s88, 0xa000000
	v_writelane_b32 v252, s2, 53
	s_addc_u32 s11, s89, 0
	s_mov_b32 s13, s21
	v_writelane_b32 v252, s3, 54
	s_add_u32 s2, s88, 0x4000000
	v_writelane_b32 v252, s2, 55
	s_addc_u32 s2, s89, 0
	v_writelane_b32 v252, s2, 56
	s_add_u32 s2, s88, 0x2000000
	v_writelane_b32 v252, s2, 57
	s_addc_u32 s2, s89, 0
	v_writelane_b32 v252, s2, 58
	s_add_u32 s2, s88, 0x1800000
	v_writelane_b32 v252, s2, 59
	s_addc_u32 s2, s89, 0
	v_writelane_b32 v252, s2, 60
	s_add_u32 s2, s88, 0x10e00000
	s_addc_u32 s3, s89, 0
	v_writelane_b32 v252, s2, 61
	s_mov_b64 s[26:27], 0x80
	s_nop 0
	v_writelane_b32 v252, s3, 62
	s_add_u32 s2, s88, 0x11f00000
	s_addc_u32 s3, s89, 0
	v_writelane_b32 v252, s2, 63
	s_nop 1
	v_writelane_b32 v253, s3, 0
	s_add_u32 s2, s88, 0x17400000
	v_writelane_b32 v253, s2, 1
	s_addc_u32 s2, s89, 0
	v_writelane_b32 v253, s2, 2
	s_add_u32 s2, s88, 0x15200000
	s_addc_u32 s3, s89, 0
	v_writelane_b32 v253, s2, 3
	s_nop 1
	v_writelane_b32 v253, s3, 4
	s_add_u32 s2, s88, 0x16300000
	s_addc_u32 s3, s89, 0
	v_writelane_b32 v253, s2, 5
	s_nop 1
	v_writelane_b32 v253, s3, 6
	s_add_u32 s2, s88, 0x18500000
	v_writelane_b32 v253, s2, 7
	s_addc_u32 s2, s89, 0
	v_writelane_b32 v253, s2, 8
	s_add_u32 s2, s88, 0x14100000
	s_addc_u32 s3, s89, 0
	v_writelane_b32 v253, s2, 9
	s_nop 1
	v_writelane_b32 v253, s3, 10
	s_add_u32 s2, s88, 0x13000000
	s_addc_u32 s3, s89, 0
	v_writelane_b32 v253, s2, 11
	s_cmpk_lt_i32 s9, 0x550
	s_nop 0
	v_writelane_b32 v253, s3, 12
	s_cselect_b64 s[2:3], -1, 0
	v_writelane_b32 v253, s2, 13
	s_nop 1
	v_writelane_b32 v253, s3, 14
	s_ashr_i32 s2, s9, 31
	v_writelane_b32 v253, s2, 15
	s_lshr_b32 s2, s2, 29
	s_add_i32 s2, s9, s2
	s_ashr_i32 s7, s2, 3
	s_and_b32 s2, s2, -8
	s_sub_i32 s5, s9, s2
	s_add_u32 s2, s88, 0x10c00000
	v_writelane_b32 v253, s2, 16
	s_addc_u32 s2, s89, 0
	s_add_u32 s52, s88, 0xec00000
	s_addc_u32 s53, s89, 0
	v_writelane_b32 v253, s2, 17
	s_add_u32 s2, s88, 0x6100000
	s_addc_u32 s3, s89, 0
	v_writelane_b32 v253, s2, 18
	s_cmpk_lt_i32 s9, 0x80
	s_nop 0
	v_writelane_b32 v253, s3, 19
	s_cselect_b64 s[2:3], -1, 0
	v_writelane_b32 v253, s2, 20
	s_lshl_b32 s4, s5, 6
	s_bfe_u32 s12, s9, 0x20002
	v_writelane_b32 v253, s3, 21
	s_ashr_i32 s2, s9, 4
	s_addk_i32 s2, 0x80
	s_ashr_i32 s3, s2, 31
	v_writelane_b32 v253, s2, 22
	s_nop 1
	v_writelane_b32 v253, s3, 23
	s_and_b32 s2, s9, 3
	s_cmp_lt_i32 s5, 0
	v_writelane_b32 v253, s2, 24
	s_cselect_b64 s[2:3], -1, 0
	v_writelane_b32 v253, s2, 25
	s_nop 1
	v_writelane_b32 v253, s3, 26
	s_and_b64 s[2:3], s[2:3], exec
	s_movk_i32 s3, 0xab
	s_cselect_b32 s3, s3, 0xaa
	s_mul_i32 s2, s5, 0x41
	s_mul_i32 s3, s5, s3
	s_cselect_b32 s2, s2, s4
	s_add_i32 s3, s3, s7
	s_mul_hi_i32 s4, s3, 0x66666667
	v_writelane_b32 v253, s5, 27
	s_lshr_b32 s5, s4, 31
	s_ashr_i32 s4, s4, 4
	s_add_i32 s4, s4, s5
	s_mul_i32 s5, s4, 40
	s_sub_i32 s3, s3, s5
	s_bfe_i32 s5, s3, 0x80000
	s_bfe_u32 s5, s5, 0x2000d
	s_add_i32 s5, s3, s5
	s_and_b32 s6, s5, 0xfc
	s_add_i32 s2, s2, s7
	s_sub_i32 s3, s3, s6
	s_ashr_i32 s6, s2, 31
	s_lshr_b32 s6, s6, 28
	s_add_i32 s6, s2, s6
	v_writelane_b32 v253, s7, 28
	s_and_b32 s7, s6, 0xfff0
	s_sub_i32 s2, s2, s7
	s_bfe_i32 s7, s2, 0x80000
	s_bfe_u32 s7, s7, 0x2000d
	s_add_i32 s7, s2, s7
	s_and_b32 s8, s7, 0xfc
	s_lshl_b32 s4, s4, 2
	s_sext_i32_i8 s3, s3
	s_sub_i32 s2, s2, s8
	s_add_i32 s14, s4, s3
	s_ashr_i32 s3, s6, 4
	s_lshl_b32 s3, s3, 2
	s_sext_i32_i8 s2, s2
	s_add_i32 s2, s3, s2
	s_bfe_i32 s4, s7, 0x80000
	s_ashr_i32 s3, s2, 31
	s_sext_i32_i16 s4, s4
	v_writelane_b32 v253, s2, 29
	s_bfe_i32 s5, s5, 0x80000
	s_sext_i32_i16 s5, s5
	v_writelane_b32 v253, s3, 30
	s_ashr_i32 s2, s4, 2
	v_writelane_b32 v253, s2, 31
	s_lshr_b32 s2, s4, 2
	s_bfe_i64 s[2:3], s[2:3], 0x100000
	v_writelane_b32 v253, s2, 32
	s_ashr_i32 s15, s14, 31
	s_nop 0
	v_writelane_b32 v253, s3, 33
	s_ashr_i32 s2, s5, 2
	v_writelane_b32 v253, s2, 34
	s_lshr_b32 s2, s5, 2
	s_bfe_i64 s[2:3], s[2:3], 0x100000
	s_lshl_b64 s[2:3], s[2:3], 19
	v_writelane_b32 v253, s2, 35
	s_nop 1
	v_writelane_b32 v253, s3, 36
	s_mov_b32 s2, s14
	v_writelane_b32 v253, s2, 37
	s_nop 1
	v_writelane_b32 v253, s3, 38
	s_lshl_b64 s[2:3], s[14:15], 19
	s_add_u32 s4, s10, s2
	v_writelane_b32 v253, s10, 39
	s_addc_u32 s5, s11, s3
	s_movk_i32 s2, 0x3ff
	v_writelane_b32 v253, s11, 40
	v_writelane_b32 v253, s12, 41
	v_and_or_b32 v0, v0, s2, v155
	s_add_u32 s2, s4, 0x40000
	v_writelane_b32 v253, s13, 42
	v_writelane_b32 v253, s4, 43
	s_addc_u32 s3, s5, 0
	s_mov_b32 s13, 0x800000
	v_writelane_b32 v253, s5, 44
	v_writelane_b32 v253, s2, 45
	s_movk_i32 s14, 0x7fff
	s_mov_b32 s15, 0x8800
	v_writelane_b32 v253, s3, 46
	s_lshl_b32 s2, s9, 10
	v_writelane_b32 v253, s2, 47
	s_lshl_b32 s2, s9, 4
	v_writelane_b32 v253, s2, 48
	s_add_u32 s2, s88, 0x16310000
	s_addc_u32 s3, s89, 0
	v_writelane_b32 v253, s2, 49
	s_mov_b32 s12, s90
	s_nop 0
	v_writelane_b32 v253, s3, 50
	s_add_u32 s2, s88, 0x18502100
	s_addc_u32 s3, s89, 0
	v_writelane_b32 v253, s2, 51
	s_nop 1
	v_writelane_b32 v253, s3, 52
	s_add_u32 s2, s88, 0x18500100
	s_addc_u32 s3, s89, 0
	v_writelane_b32 v253, s2, 53
	s_nop 1
	v_writelane_b32 v253, s3, 54
	s_add_u32 s2, s88, 0x20080
	v_writelane_b32 v253, s2, 55
	s_addc_u32 s2, s89, 0
	v_writelane_b32 v253, s2, 56
	s_add_u32 s2, s88, 0x100
	v_writelane_b32 v253, s2, 57
	s_addc_u32 s2, s89, 0
	v_writelane_b32 v253, s2, 58
	s_add_i32 s2, 0, 0x20010
	v_writelane_b32 v253, s2, 59
	s_add_i32 s2, 0, 0x20014
	v_writelane_b32 v253, s2, 60
	s_add_i32 s2, 0, 0x20000
	v_writelane_b32 v253, s2, 61
	s_add_i32 s2, 0, 0x21c00
	v_writelane_b32 v253, s2, 62
	s_add_i32 s2, 0, 0x21400
	v_writelane_b32 v253, s2, 63
	s_add_i32 s2, 0, 0x217a0
	v_writelane_b32 v254, s2, 0
	s_add_i32 s2, 0, 0x11100
	v_writelane_b32 v254, s2, 1
	v_cmp_eq_u32_e64 s[2:3], 0, v0
	s_nop 1
	v_writelane_b32 v254, s2, 2
	s_nop 1
	v_writelane_b32 v254, s3, 3
	v_writelane_b32 v254, s56, 4
	s_nop 1
	v_writelane_b32 v254, s57, 5
	v_writelane_b32 v254, s58, 6
	v_writelane_b32 v254, s59, 7
	v_writelane_b32 v254, s60, 8
	v_writelane_b32 v254, s61, 9
	v_writelane_b32 v254, s62, 10
	v_writelane_b32 v254, s63, 11
	v_writelane_b32 v254, s64, 12
	v_writelane_b32 v254, s65, 13
	v_writelane_b32 v254, s66, 14
	v_writelane_b32 v254, s67, 15
	v_writelane_b32 v254, s68, 16
	v_writelane_b32 v254, s69, 17
	v_writelane_b32 v254, s70, 18
	v_writelane_b32 v254, s71, 19
	v_writelane_b32 v254, s0, 20
	v_readlane_b32 s56, v252, 35
	v_readlane_b32 s57, v252, 36
	v_writelane_b32 v254, s1, 21
	v_writelane_b32 v254, s2, 22
	v_writelane_b32 v254, s3, 23
	v_writelane_b32 v254, s4, 24
	v_writelane_b32 v254, s5, 25
	v_writelane_b32 v254, s6, 26
	v_writelane_b32 v254, s7, 27
	v_writelane_b32 v254, s8, 28
	v_writelane_b32 v254, s9, 29
	v_writelane_b32 v254, s10, 30
	v_writelane_b32 v254, s11, 31
	v_writelane_b32 v254, s12, 32
	v_writelane_b32 v254, s13, 33
	v_writelane_b32 v254, s14, 34
	v_writelane_b32 v254, s15, 35
	v_writelane_b32 v254, s42, 36
	v_readlane_b32 s58, v252, 37
	v_readlane_b32 s59, v252, 38
	v_writelane_b32 v254, s43, 37
	v_writelane_b32 v254, s72, 38
	v_readlane_b32 s66, v252, 45
	v_readlane_b32 s67, v252, 46
	v_writelane_b32 v254, s73, 39
	v_writelane_b32 v254, s74, 40
	v_writelane_b32 v254, s75, 41
	v_writelane_b32 v254, s76, 42
	v_writelane_b32 v254, s77, 43
	v_writelane_b32 v254, s78, 44
	v_writelane_b32 v254, s79, 45
	v_writelane_b32 v254, s80, 46
	v_writelane_b32 v254, s81, 47
	v_writelane_b32 v254, s82, 48
	v_writelane_b32 v254, s83, 49
	v_writelane_b32 v254, s84, 50
	v_writelane_b32 v254, s85, 51
	v_writelane_b32 v254, s86, 52
	v_readlane_b32 s70, v252, 49
	v_readlane_b32 s71, v252, 50
	v_writelane_b32 v254, s87, 53
	v_readlane_b32 s60, v252, 39
	v_readlane_b32 s61, v252, 40
	v_readlane_b32 s62, v252, 41
	v_readlane_b32 s63, v252, 42
	v_readlane_b32 s64, v252, 43
	v_readlane_b32 s65, v252, 44
	v_readlane_b32 s68, v252, 47
	v_readlane_b32 s69, v252, 48
	s_branch .LBB0_9

.LBB0_8:
	s_cmp_eq_u32 s12, 2
	s_cbranch_scc0 .Lmy_tf_done
	v_readlane_b32 s41, v251, 0
	s_cmp_lt_u32 s41, 0x50
	s_cbranch_scc1 .Lmy_tf_done
	s_add_i32 s41, s41, 0x30
	s_mov_b32 s32, 0
	s_mov_b64 s[38:39], exec
	s_mov_b64 exec, -1
	s_waitcnt vmcnt(0) lgkmcnt(0)
	s_sub_u32 s98, s96, 0xd0
	s_subb_u32 s99, s97, 0
	s_load_dwordx2 s[60:61], s[98:99], 0x40
	s_load_dwordx2 s[62:63], s[98:99], 0x48
	s_load_dwordx2 s[64:65], s[98:99], 0xa0
	s_load_dwordx2 s[68:69], s[98:99], 0xa8
	v_readfirstlane_b32 s44, v155
	s_lshr_b32 s44, s44, 6
	v_and_b32_e32 v102, 63, v155
	v_lshlrev_b32_e32 v103, 4, v102
	s_waitcnt lgkmcnt(0)
	s_add_i32 s46, s41, 0x0
	s_cmp_lt_u32 s46, 0x80
	s_cbranch_scc0 .Lmy_tf0_s1
	s_lshr_b32 s16, s46, 3
	s_and_b32 s18, s46, 7
	s_mul_i32 s20, s32, 0x900000
	s_add_u32 s0, s60, s20
	s_addc_u32 s1, s61, 0
	s_add_u32 s0, s0, 0x400
	s_addc_u32 s1, s1, 0
	s_mul_i32 s20, s32, 0x500000
	s_add_u32 s20, s20, 0x500000
	s_movk_i32 s4, 0x2400
	s_movk_i32 s6, 0x800
	s_mov_b32 s50, 13
	s_branch .Lmy_tf0_sd

.Lmy_tf2_sd:
	s_add_u32 s2, s88, s20
	s_addc_u32 s3, s89, 0
	s_lshl_b32 s48, s18, 8
	s_mul_i32 s48, s48, s6
	s_lshl_b32 s20, s16, 7
	s_add_u32 s48, s48, s20
	s_lshl_b32 s20, s44, 4
	s_add_u32 s48, s48, s20
	s_add_u32 s2, s2, s48
	s_addc_u32 s3, s3, 0
	s_lshl_b32 s20, s16, 6
	s_lshl_b32 s48, s44, 3
	s_add_u32 s20, s20, s48
	s_mul_i32 s20, s20, s4
	s_lshl_b32 s48, s18, 10
	s_add_u32 s20, s20, s48
	s_add_u32 s0, s0, s20
	s_addc_u32 s1, s1, 0
	v_lshlrev_b32_e32 v104, s50, v102
	global_load_dwordx4 v[118:121], v103, s[0:1] nt
	s_add_u32 s0, s0, s4
	s_addc_u32 s1, s1, 0
	global_load_dwordx4 v[122:125], v103, s[0:1] nt
	s_add_u32 s0, s0, s4
	s_addc_u32 s1, s1, 0
	global_load_dwordx4 v[126:129], v103, s[0:1] nt
	s_add_u32 s0, s0, s4
	s_addc_u32 s1, s1, 0
	global_load_dwordx4 v[130:133], v103, s[0:1] nt
	s_add_u32 s0, s0, s4
	s_addc_u32 s1, s1, 0
	global_load_dwordx4 v[134:137], v103, s[0:1] nt
	s_add_u32 s0, s0, s4
	s_addc_u32 s1, s1, 0
	global_load_dwordx4 v[138:141], v103, s[0:1] nt
	s_add_u32 s0, s0, s4
	s_addc_u32 s1, s1, 0
	global_load_dwordx4 v[142:145], v103, s[0:1] nt
	s_add_u32 s0, s0, s4
	s_addc_u32 s1, s1, 0
	global_load_dwordx4 v[146:149], v103, s[0:1] nt
	s_waitcnt vmcnt(12)
	v_cvt_pk_bf16_f32 v234, v176, v180
	v_cvt_pk_bf16_f32 v235, v184, v188
	v_cvt_pk_bf16_f32 v236, v192, v196
	v_cvt_pk_bf16_f32 v237, v200, v204
	v_cvt_pk_bf16_f32 v238, v177, v181
	v_cvt_pk_bf16_f32 v239, v185, v189
	v_cvt_pk_bf16_f32 v240, v193, v197
	v_cvt_pk_bf16_f32 v241, v201, v205
	v_cvt_pk_bf16_f32 v242, v178, v182
	v_cvt_pk_bf16_f32 v243, v186, v190
	v_cvt_pk_bf16_f32 v244, v194, v198
	v_cvt_pk_bf16_f32 v245, v202, v206
	v_cvt_pk_bf16_f32 v246, v179, v183
	v_cvt_pk_bf16_f32 v247, v187, v191
	v_cvt_pk_bf16_f32 v248, v195, v199
	v_cvt_pk_bf16_f32 v249, v203, v207
	global_store_dwordx4 v105, v[234:237], s[10:11]
	s_add_u32 s10, s10, s9
	s_addc_u32 s11, s11, 0
	global_store_dwordx4 v105, v[238:241], s[10:11]
	s_add_u32 s10, s10, s9
	s_addc_u32 s11, s11, 0
	global_store_dwordx4 v105, v[242:245], s[10:11]
	s_add_u32 s10, s10, s9
	s_addc_u32 s11, s11, 0
	global_store_dwordx4 v105, v[246:249], s[10:11]
	s_cmp_lt_u32 s41, 0xb0
	s_cbranch_scc0 .Lmy_tf_no4
	s_add_i32 s46, s41, 0x210
	s_cmp_lt_u32 s46, 0x80
	s_cbranch_scc0 .Lmy_tf3_s1
	s_lshr_b32 s16, s46, 3
	s_and_b32 s18, s46, 7
	s_mul_i32 s20, s32, 0x900000
	s_add_u32 s0, s60, s20
	s_addc_u32 s1, s61, 0
	s_add_u32 s0, s0, 0x400
	s_addc_u32 s1, s1, 0
	s_mul_i32 s20, s32, 0x500000
	s_add_u32 s20, s20, 0x500000
	s_movk_i32 s4, 0x2400
	s_movk_i32 s9, 0x800
	s_mov_b32 s50, 13
	s_branch .Lmy_tf3_sd

.Lmy_tf3_sd:
	s_add_u32 s10, s88, s20
	s_addc_u32 s11, s89, 0
	s_lshl_b32 s48, s18, 8
	s_mul_i32 s48, s48, s9
	s_lshl_b32 s20, s16, 7
	s_add_u32 s48, s48, s20
	s_lshl_b32 s20, s44, 4
	s_add_u32 s48, s48, s20
	s_add_u32 s10, s10, s48
	s_addc_u32 s11, s11, 0
	s_lshl_b32 s20, s16, 6
	s_lshl_b32 s48, s44, 3
	s_add_u32 s20, s20, s48
	s_mul_i32 s20, s20, s4
	s_lshl_b32 s48, s18, 10
	s_add_u32 s20, s20, s48
	s_add_u32 s0, s0, s20
	s_addc_u32 s1, s1, 0
	v_lshlrev_b32_e32 v105, s50, v102
	global_load_dwordx4 v[176:179], v103, s[0:1] nt
	s_add_u32 s0, s0, s4
	s_addc_u32 s1, s1, 0
	global_load_dwordx4 v[180:183], v103, s[0:1] nt
	s_add_u32 s0, s0, s4
	s_addc_u32 s1, s1, 0
	global_load_dwordx4 v[184:187], v103, s[0:1] nt
	s_add_u32 s0, s0, s4
	s_addc_u32 s1, s1, 0
	global_load_dwordx4 v[188:191], v103, s[0:1] nt
	s_add_u32 s0, s0, s4
	s_addc_u32 s1, s1, 0
	global_load_dwordx4 v[192:195], v103, s[0:1] nt
	s_add_u32 s0, s0, s4
	s_addc_u32 s1, s1, 0
	global_load_dwordx4 v[196:199], v103, s[0:1] nt
	s_add_u32 s0, s0, s4
	s_addc_u32 s1, s1, 0
	global_load_dwordx4 v[200:203], v103, s[0:1] nt
	s_add_u32 s0, s0, s4
	s_addc_u32 s1, s1, 0
	global_load_dwordx4 v[204:207], v103, s[0:1] nt
	s_waitcnt vmcnt(12)
	v_cvt_pk_bf16_f32 v80, v118, v122
	v_cvt_pk_bf16_f32 v81, v126, v130
	v_cvt_pk_bf16_f32 v82, v134, v138
	v_cvt_pk_bf16_f32 v83, v142, v146
	v_cvt_pk_bf16_f32 v84, v119, v123
	v_cvt_pk_bf16_f32 v85, v127, v131
	v_cvt_pk_bf16_f32 v86, v135, v139
	v_cvt_pk_bf16_f32 v87, v143, v147
	v_cvt_pk_bf16_f32 v88, v120, v124
	v_cvt_pk_bf16_f32 v89, v128, v132
	v_cvt_pk_bf16_f32 v90, v136, v140
	v_cvt_pk_bf16_f32 v91, v144, v148
	v_cvt_pk_bf16_f32 v92, v121, v125
	v_cvt_pk_bf16_f32 v93, v129, v133
	v_cvt_pk_bf16_f32 v94, v137, v141
	v_cvt_pk_bf16_f32 v95, v145, v149
	global_store_dwordx4 v104, v[80:83], s[2:3]
	s_add_u32 s2, s2, s6
	s_addc_u32 s3, s3, 0
	global_store_dwordx4 v104, v[84:87], s[2:3]
	s_add_u32 s2, s2, s6
	s_addc_u32 s3, s3, 0
	global_store_dwordx4 v104, v[88:91], s[2:3]
	s_add_u32 s2, s2, s6
	s_addc_u32 s3, s3, 0
	global_store_dwordx4 v104, v[92:95], s[2:3]
	s_waitcnt vmcnt(4)
	v_cvt_pk_bf16_f32 v234, v176, v180
	v_cvt_pk_bf16_f32 v235, v184, v188
	v_cvt_pk_bf16_f32 v236, v192, v196
	v_cvt_pk_bf16_f32 v237, v200, v204
	v_cvt_pk_bf16_f32 v238, v177, v181
	v_cvt_pk_bf16_f32 v239, v185, v189
	v_cvt_pk_bf16_f32 v240, v193, v197
	v_cvt_pk_bf16_f32 v241, v201, v205
	v_cvt_pk_bf16_f32 v242, v178, v182
	v_cvt_pk_bf16_f32 v243, v186, v190
	v_cvt_pk_bf16_f32 v244, v194, v198
	v_cvt_pk_bf16_f32 v245, v202, v206
	v_cvt_pk_bf16_f32 v246, v179, v183
	v_cvt_pk_bf16_f32 v247, v187, v191
	v_cvt_pk_bf16_f32 v248, v195, v199
	v_cvt_pk_bf16_f32 v249, v203, v207
	global_store_dwordx4 v105, v[234:237], s[10:11]
	s_add_u32 s10, s10, s9
	s_addc_u32 s11, s11, 0
	global_store_dwordx4 v105, v[238:241], s[10:11]
	s_add_u32 s10, s10, s9
	s_addc_u32 s11, s11, 0
	global_store_dwordx4 v105, v[242:245], s[10:11]
	s_add_u32 s10, s10, s9
	s_addc_u32 s11, s11, 0
	global_store_dwordx4 v105, v[246:249], s[10:11]
	s_branch .Lmy_tf_end
.Lmy_tf_no4:
	s_waitcnt vmcnt(4)
	v_cvt_pk_bf16_f32 v80, v118, v122
	v_cvt_pk_bf16_f32 v81, v126, v130
	v_cvt_pk_bf16_f32 v82, v134, v138
	v_cvt_pk_bf16_f32 v83, v142, v146
	v_cvt_pk_bf16_f32 v84, v119, v123
	v_cvt_pk_bf16_f32 v85, v127, v131
	v_cvt_pk_bf16_f32 v86, v135, v139
	v_cvt_pk_bf16_f32 v87, v143, v147
	v_cvt_pk_bf16_f32 v88, v120, v124
	v_cvt_pk_bf16_f32 v89, v128, v132
	v_cvt_pk_bf16_f32 v90, v136, v140
	v_cvt_pk_bf16_f32 v91, v144, v148
	v_cvt_pk_bf16_f32 v92, v121, v125
	v_cvt_pk_bf16_f32 v93, v129, v133
	v_cvt_pk_bf16_f32 v94, v137, v141
	v_cvt_pk_bf16_f32 v95, v145, v149
	global_store_dwordx4 v104, v[80:83], s[2:3]
	s_add_u32 s2, s2, s6
	s_addc_u32 s3, s3, 0
	global_store_dwordx4 v104, v[84:87], s[2:3]
	s_add_u32 s2, s2, s6
	s_addc_u32 s3, s3, 0
	global_store_dwordx4 v104, v[88:91], s[2:3]
	s_add_u32 s2, s2, s6
	s_addc_u32 s3, s3, 0
	global_store_dwordx4 v104, v[92:95], s[2:3]
.Lmy_tf_end:
	s_mov_b64 exec, s[38:39]
	s_nop 0
	s_nop 0
	s_nop 0
	s_nop 0
	s_nop 0
	s_nop 0
	s_nop 0
	s_nop 0
	s_nop 0
	s_nop 0
	s_nop 0
	s_nop 0
	s_nop 0
	s_nop 0
	s_nop 0
	s_nop 0
	s_nop 0
	s_nop 0
	s_nop 0
	s_nop 0
	s_nop 0
	s_nop 0
	s_nop 0
	s_nop 0
	s_nop 0
	s_nop 0
	s_nop 0
	s_nop 0
	s_nop 0

.LBB0_631:
	s_lshl_b32 s19, s18, 3
	s_lshl_b32 s20, s2, 3
	s_add_i32 s22, s20, s10
	s_add_i32 s23, s19, s6
	s_add_i32 s24, s20, s12
	s_add_i32 s25, s19, s11
	s_add_i32 s28, s20, s15
	s_add_i32 s29, s19, s14
	s_add_i32 s20, s20, s17
	s_add_i32 s19, s19, s16
	v_lshl_add_u32 v0, s23, 2, v7
	v_lshl_add_u32 v8, s22, 2, v7
	s_add_i32 s22, s22, s9
	s_add_i32 s23, s23, s8
	v_lshl_add_u32 v9, s25, 2, v7
	s_add_i32 s30, s24, s9
	s_add_i32 s25, s25, s8
	v_lshl_add_u32 v11, s29, 2, v7
	s_add_i32 s31, s28, s9
	s_add_i32 s29, s29, s8
	v_lshl_add_u32 v13, s19, 2, v7
	v_lshl_add_u32 v14, s20, 2, v7
	s_add_i32 s20, s20, s9
	s_add_i32 s19, s19, s8
	v_lshl_add_u32 v10, s24, 2, v7
	v_lshl_add_u32 v12, s28, 2, v7
	s_ashr_i32 s35, s23, 31
	s_ashr_i32 s37, s22, 31
	s_mul_hi_u32 s42, s0, s23
	s_mul_i32 s43, s1, s23
	s_mul_i32 s24, s0, s23
	s_ashr_i32 s23, s25, 31
	s_ashr_i32 s44, s30, 31
	s_mul_hi_u32 s45, s3, s30
	s_mul_i32 s46, s7, s30
	s_mul_i32 s28, s3, s30
	s_mul_hi_u32 s47, s0, s25
	s_mul_i32 s48, s1, s25
	s_mul_i32 s30, s0, s25
	s_ashr_i32 s25, s29, 31
	s_ashr_i32 s49, s31, 31
	s_mul_hi_u32 s50, s3, s31
	s_mul_i32 s51, s7, s31
	s_mul_i32 s34, s3, s31
	s_mul_hi_u32 s31, s0, s29
	s_mul_i32 s92, s1, s29
	s_mul_i32 s36, s0, s29
	ds_read_b32 v0, v0 offset:53248
	ds_read_b32 v24, v8 offset:53248
	ds_read_b32 v25, v9 offset:53248
	ds_read_b32 v26, v10 offset:53248
	ds_read_b32 v27, v11 offset:53248
	ds_read_b32 v28, v12 offset:53248
	ds_read_b32 v29, v13 offset:53248
	ds_read_b32 v30, v14 offset:53248
	s_ashr_i32 s29, s19, 31
	s_ashr_i32 s93, s20, 31
	s_mul_hi_u32 s39, s3, s22
	s_mul_hi_u32 s94, s3, s20
	s_mul_i32 s95, s7, s20
	s_mul_i32 s38, s3, s20
	s_mul_hi_u32 s20, s0, s19
	s_mul_i32 vcc_lo, s1, s19
	s_mul_i32 s40, s0, s19
	s_mul_i32 s19, s3, s37
	s_mul_i32 s35, s0, s35
	s_mul_i32 s37, s3, s44
	s_mul_i32 s23, s0, s23
	s_mul_i32 s44, s3, s49
	s_mul_i32 s25, s0, s25
	s_mul_i32 s49, s3, s93
	s_mul_i32 s29, s0, s29
	s_mul_i32 s41, s7, s22
	s_add_i32 s19, s39, s19
	s_add_i32 s35, s42, s35
	s_add_i32 s37, s45, s37
	s_add_i32 s39, s47, s23
	s_add_i32 s42, s50, s44
	s_add_i32 s44, s31, s25
	s_add_i32 s45, s94, s49
	s_add_i32 s20, s20, s29
	s_add_i32 s18, s18, 8
	s_add_i32 s2, s2, 8
	s_add_i32 s13, s13, -8
	s_add_i32 s23, s19, s41
	s_add_i32 s25, s35, s43
	s_add_i32 s29, s37, s46
	s_add_i32 s31, s39, s48
	s_add_i32 s35, s42, s51
	s_add_i32 s37, s44, s92
	s_add_i32 s39, s45, s95
	s_add_i32 s41, s20, vcc_lo
	s_mul_i32 s22, s3, s22
	v_lshl_add_u64 v[8:9], s[24:25], 1, v[2:3]
	s_cmp_lg_u32 s13, 0
	s_waitcnt lgkmcnt(6)
	v_cvt_pk_bf16_f32 v0, v0, v24
	v_lshl_add_u64 v[10:11], s[22:23], 1, v[2:3]
	v_lshl_add_u64 v[12:13], s[30:31], 1, v[2:3]
	v_lshl_add_u64 v[14:15], s[28:29], 1, v[2:3]
	v_lshl_add_u64 v[16:17], s[36:37], 1, v[2:3]
	v_lshl_add_u64 v[18:19], s[34:35], 1, v[2:3]
	v_lshl_add_u64 v[20:21], s[40:41], 1, v[2:3]
	v_lshl_add_u64 v[22:23], s[38:39], 1, v[2:3]
	s_waitcnt lgkmcnt(4)
	v_cvt_pk_bf16_f32 v24, v25, v26
	s_waitcnt lgkmcnt(2)
	v_cvt_pk_bf16_f32 v25, v27, v28
	s_waitcnt lgkmcnt(0)
	v_cvt_pk_bf16_f32 v26, v29, v30
	global_store_short v[8:9], v0, off
	global_store_short_d16_hi v[10:11], v0, off
	global_store_short v[12:13], v24, off
	global_store_short_d16_hi v[14:15], v24, off
	global_store_short v[16:17], v25, off
	global_store_short_d16_hi v[18:19], v25, off
	global_store_short v[20:21], v26, off
	global_store_short_d16_hi v[22:23], v26, off
	s_cbranch_scc1 .LBB0_631
	s_load_dword s0, s[96:97], 0x0
	v_readlane_b32 s42, v254, 36
	v_readlane_b32 s43, v254, 37
	s_mov_b32 s40, 0x8000
	s_mov_b32 s13, 0x800000
	s_waitcnt lgkmcnt(0)
	s_add_i32 s4, s4, s0
	s_cmpk_lt_i32 s4, 0x80
	s_movk_i32 s14, 0x7fff
	s_mov_b32 s15, 0x8800
	v_readlane_b32 s12, v254, 54
	s_cbranch_scc1 .LBB0_620
	s_branch .LBB0_635
